# row-scale table build skips the reload when consecutive tiles share the token tile (in-proj, up-proj)
# baseline (speedup 1.0000x reference)
.LBB0_41:
	v_readlane_b32 s8, v250, 11
	v_readlane_b32 s9, v250, 12
	s_load_dwordx2 s[22:23], s[8:9], 0x88
	v_mov_b32_e32 v2, v199
	s_movk_i32 s4, 0x100
	v_ashrrev_i32_e32 v3, 31, v2
	s_waitcnt lgkmcnt(0)
	s_add_u32 s6, s22, s66
	s_addc_u32 s7, s23, s67
	v_lshl_add_u64 v[0:1], v[2:3], 3, s[6:7]
	v_readlane_b32 s6, v250, 44
	v_cmp_gt_i32_e64 s[4:5], s4, v2
	v_add_u32_e32 v4, 0xfffffe00, v2
	v_lshl_add_u32 v5, v2, 2, s6
	s_mov_b32 s10, s55
	s_mov_b32 s21, -1
	s_branch .LBB0_44

.LBB0_47:
	s_and_saveexec_b64 s[6:7], s[4:5]
	s_cbranch_execz .LBB0_42
	s_cmp_eq_u32 s76, s21
	s_cbranch_scc1 .Lrs_reuse_in
	s_mov_b32 s21, s76
	s_ashr_i32 s77, s76, 31
	s_lshl_b64 s[12:13], s[76:77], 11
	v_lshl_add_u64 v[2:3], v[0:1], 0, s[12:13]
	s_mov_b64 s[12:13], 0
	v_mov_b32_e32 v6, v5
	v_mov_b32_e32 v7, v4

.Lrs_reuse_in:
	ds_write_b32 v5, v8
	s_branch .LBB0_42

.LBB0_556:
	s_or_b64 exec, exec, s[6:7]
	v_readlane_b32 s4, v250, 11
	v_readlane_b32 s5, v250, 12
	s_waitcnt lgkmcnt(0)
	s_barrier
	s_load_dwordx2 s[14:15], s[4:5], 0x88
	v_mov_b32_e32 v2, v199
	s_movk_i32 s4, 0x100
	s_nop 0
	v_cmp_gt_i32_e64 s[6:7], s4, v2
	s_waitcnt lgkmcnt(0)
	s_add_u32 s4, s14, s60
	v_ashrrev_i32_e32 v3, 31, v2
	s_addc_u32 s5, s15, s61
	v_lshl_add_u64 v[0:1], v[2:3], 3, s[4:5]
	v_readlane_b32 s4, v250, 44
	v_add_u32_e32 v4, 0xfffffe00, v2
	s_nop 0
	v_lshl_add_u32 v5, v2, 2, s4
	s_mov_b32 s4, 0
	s_mov_b32 s21, -1
	s_branch .LBB0_559

.LBB0_566:
	s_and_saveexec_b64 s[8:9], s[6:7]
	s_cbranch_execz .LBB0_557
	s_cmp_eq_u32 s80, s21
	s_cbranch_scc1 .Lrs_reuse_up
	s_mov_b32 s21, s80
	s_ashr_i32 s81, s80, 31
	s_lshl_b64 s[10:11], s[80:81], 11
	v_lshl_add_u64 v[2:3], v[0:1], 0, s[10:11]
	s_mov_b64 s[12:13], 0
	v_mov_b32_e32 v6, v5
	v_mov_b32_e32 v7, v4
